# diff attention fast loop: softmax row sums via 8 two-pass 4x4x4 bf16 MFMAs (ones x P, lane-local f32 accumulators) instead of 4 eight-pass 32x32x16 ones MFMAs; folded into the replicated l registers a
# speedup vs baseline: 1.0238x; 1.0206x over previous
.Lf_459:
	v_mov_b32_e32 v180, v128
	v_mov_b32_e32 v181, v129
	v_mov_b32_e32 v182, v130
	v_mov_b32_e32 v183, v131
	v_mfma_f32_32x32x16_bf16 v[64:79], v[176:179], v[140:143], v[64:79]
	ds_read_b64_tr_b16 v[128:129], v0 offset:24576
	ds_read_b64_tr_b16 v[130:131], v0 offset:25088
	v_exp_f32_e32 v14, v112
	v_mfma_f32_32x32x16_bf16 v[64:79], v[172:175], v[136:139], v[64:79]
	ds_read_b64_tr_b16 v[172:173], v0 offset:25600
	ds_read_b64_tr_b16 v[174:175], v0 offset:26112
	v_exp_f32_e32 v15, v96
	v_mfma_f32_32x32x16_bf16 v[64:79], v[168:171], v[132:135], v[64:79]
	ds_read_b64_tr_b16 v[168:169], v0 offset:26624
	ds_read_b64_tr_b16 v[170:171], v0 offset:27136
	v_exp_f32_e32 v96, v113
	v_mfma_f32_32x32x16_bf16 v[64:79], v[164:167], v[180:183], v[64:79]
	ds_read_b64_tr_b16 v[164:165], v0 offset:27648
	ds_read_b64_tr_b16 v[166:167], v0 offset:28160
	v_exp_f32_e32 v97, v97
	v_mfma_f32_32x32x16_bf16 v[48:63], v[160:163], v[140:143], v[48:63]
	ds_read_b64_tr_b16 v[160:161], v0 offset:28672
	ds_read_b64_tr_b16 v[162:163], v0 offset:29184
	v_exp_f32_e32 v112, v114
	v_mfma_f32_32x32x16_bf16 v[48:63], v[10:13], v[136:139], v[48:63]
	ds_read_b64_tr_b16 v[10:11], v0 offset:29696
	ds_read_b64_tr_b16 v[12:13], v0 offset:30208
	v_exp_f32_e32 v98, v98
	v_mfma_f32_32x32x16_bf16 v[48:63], v[6:9], v[132:135], v[48:63]
	ds_read_b64_tr_b16 v[6:7], v0 offset:30720
	ds_read_b64_tr_b16 v[8:9], v0 offset:31232
	v_exp_f32_e32 v113, v115
	v_mfma_f32_32x32x16_bf16 v[48:63], v[2:5], v[180:183], v[48:63]
	ds_read_b64_tr_b16 v[2:3], v0 offset:31744
	ds_read_b64_tr_b16 v[4:5], v0 offset:32256
	v_exp_f32_e32 v0, v99
	s_waitcnt lgkmcnt(14)
	v_mfma_f32_32x32x16_bf16 v[32:47], v[128:131], v[140:143], v[32:47]
	v_exp_f32_e32 v99, v116
	v_exp_f32_e32 v100, v100
	v_exp_f32_e32 v114, v117
	s_waitcnt lgkmcnt(12)
	v_mfma_f32_32x32x16_bf16 v[32:47], v[172:175], v[136:139], v[32:47]
	v_exp_f32_e32 v101, v101
	v_exp_f32_e32 v115, v118
	v_exp_f32_e32 v102, v102
	s_waitcnt lgkmcnt(10)
	v_mfma_f32_32x32x16_bf16 v[32:47], v[168:171], v[132:135], v[32:47]
	v_exp_f32_e32 v116, v119
	v_exp_f32_e32 v103, v103
	v_exp_f32_e32 v117, v120
	s_waitcnt lgkmcnt(8)
	v_mfma_f32_32x32x16_bf16 v[32:47], v[164:167], v[180:183], v[32:47]
	v_exp_f32_e32 v104, v104
	v_exp_f32_e32 v118, v121
	v_exp_f32_e32 v105, v105
	s_waitcnt lgkmcnt(6)
	v_mfma_f32_32x32x16_bf16 v[16:31], v[160:163], v[140:143], v[16:31]
	v_exp_f32_e32 v119, v122
	v_exp_f32_e32 v106, v106
	v_exp_f32_e32 v120, v123
	s_waitcnt lgkmcnt(4)
	v_mfma_f32_32x32x16_bf16 v[16:31], v[10:13], v[136:139], v[16:31]
	v_exp_f32_e32 v10, v107
	v_exp_f32_e32 v11, v124
	v_exp_f32_e32 v12, v108
	s_waitcnt lgkmcnt(2)
	v_mfma_f32_32x32x16_bf16 v[16:31], v[6:9], v[132:135], v[16:31]
	v_exp_f32_e32 v6, v125
	v_exp_f32_e32 v7, v109
	v_exp_f32_e32 v8, v126
	s_waitcnt lgkmcnt(0)
	v_mfma_f32_32x32x16_bf16 v[16:31], v[2:5], v[180:183], v[16:31]
	v_exp_f32_e32 v107, v110
	s_nop 0
	v_mfma_f32_4x4x4_16b_bf16 v[84:87], v[218:219], v[140:141], v[84:87]
	v_mfma_f32_4x4x4_16b_bf16 v[88:91], v[218:219], v[142:143], v[88:91]
	v_exp_f32_e32 v108, v127
	v_exp_f32_e32 v109, v111
	v_cvt_pk_bf16_f32 v140, v14, v96
	v_cvt_pk_bf16_f32 v143, v115, v116
	v_mfma_f32_4x4x4_16b_bf16 v[84:87], v[218:219], v[136:137], v[84:87]
	v_mfma_f32_4x4x4_16b_bf16 v[88:91], v[218:219], v[138:139], v[88:91]
	v_cvt_pk_bf16_f32 v128, v104, v105
	v_cvt_pk_bf16_f32 v141, v112, v113
	v_cvt_pk_bf16_f32 v136, v117, v118
	v_mfma_f32_4x4x4_16b_bf16 v[84:87], v[218:219], v[132:133], v[84:87]
	v_mfma_f32_4x4x4_16b_bf16 v[88:91], v[218:219], v[134:135], v[88:91]
	v_cvt_pk_bf16_f32 v137, v119, v120
	v_cvt_pk_bf16_f32 v129, v106, v10
	v_cvt_pk_bf16_f32 v132, v15, v97
	v_cvt_pk_bf16_f32 v130, v12, v7
	v_cvt_pk_bf16_f32 v138, v11, v6
	v_cvt_pk_bf16_f32 v133, v98, v0
	v_cvt_pk_bf16_f32 v142, v99, v114
	v_cvt_pk_bf16_f32 v134, v100, v101
	v_cvt_pk_bf16_f32 v135, v102, v103
	v_cvt_pk_bf16_f32 v139, v8, v108
	v_cvt_pk_bf16_f32 v131, v107, v109
	v_mfma_f32_4x4x4_16b_bf16 v[84:87], v[218:219], v[180:181], v[84:87]
	v_mfma_f32_4x4x4_16b_bf16 v[88:91], v[218:219], v[182:183], v[88:91]
	s_add_i32 s28, s28, 1
	s_add_i32 s13, s13, 1
	s_add_i32 s19, s19, 0x8000
	s_cmpk_eq_i32 s13, 0x45
	s_cbranch_scc1 .Lf_fold464

.Lf_foldrare:
	s_nop 4
	v_add_f32_e32 v84, v84, v88
	s_nop 0
	v_mov_b32_e32 v88, v84
	s_nop 1
	v_permlane32_swap_b32_e32 v88, v84
	s_nop 1
	v_add_f32_e32 v80, v84, v88
	s_nop 0
	v_mov_b32_e32 v81, v80
	v_mov_b32_e32 v82, v80
	v_mov_b32_e32 v83, v80
	v_mov_b32_e32 v84, v80
	v_mov_b32_e32 v85, v80
	v_mov_b32_e32 v86, v80
	v_mov_b32_e32 v87, v80
	v_mov_b32_e32 v88, v80
	v_mov_b32_e32 v89, v80
	v_mov_b32_e32 v90, v80
	v_mov_b32_e32 v91, v80
	v_mov_b32_e32 v92, v80
	v_mov_b32_e32 v93, v80
	v_mov_b32_e32 v94, v80
	v_mov_b32_e32 v95, v80
	s_nop 1
	s_branch .Lf_to463
.Lf_fold464:
	s_nop 4
	v_add_f32_e32 v84, v84, v88
	s_nop 0
	v_mov_b32_e32 v88, v84
	s_nop 1
	v_permlane32_swap_b32_e32 v88, v84
	s_nop 1
	v_add_f32_e32 v80, v84, v88
	s_nop 0
	v_mov_b32_e32 v81, v80
	v_mov_b32_e32 v82, v80
	v_mov_b32_e32 v83, v80
	v_mov_b32_e32 v84, v80
	v_mov_b32_e32 v85, v80
	v_mov_b32_e32 v86, v80
	v_mov_b32_e32 v87, v80
	v_mov_b32_e32 v88, v80
	v_mov_b32_e32 v89, v80
	v_mov_b32_e32 v90, v80
	v_mov_b32_e32 v91, v80
	v_mov_b32_e32 v92, v80
	v_mov_b32_e32 v93, v80
	v_mov_b32_e32 v94, v80
	v_mov_b32_e32 v95, v80
	s_nop 1
	s_branch .LBB0_464
	.p2align 6
